# v11 plus skipping the two already-satisfied DMA waits of the first K-loop trip after each epilogue
# speedup vs baseline: 1.0012x; 1.0012x over previous
; __device__ __forceinline__ float bflo(unsigned w) { return __uint_as_float(w << 16); }
; __device__ __forceinline__ float bfhi(unsigned w) { return __uint_as_float(w & 0xffff0000u); }
; __device__ __forceinline__ u32x4 pk8(const f32x4 a, const f32x4 b) { u32x4 w; w.x = pkbf(a[0], a[1]); w.y = pkbf(a[2], a[3]); w.z = pkbf(b[0], b[1]); w.w = pkbf(b[2], b[3]); return w; }
; __device__ __forceinline__ float sumsq4(const f32x4 a) { return (a[0] * a[0] + a[1] * a[1]) + (a[2] * a[2] + a[3] * a[3]); }
;     __device__ __forceinline__ void operator()(const f32x4 (&acc)[2][2][4][2], const Unit& u, int wr, int wc, int fr, int fq) const {
;         const int row0 = u.pm * BM + wr * 64 + fr, col0 = u.pn * BM + wc * 32 + 8 * fq;
; #pragma unroll
;         for (int ai = 0; ai < 2; ++ai)
; #pragma unroll
;             for (int m = 0; m < 4; ++m) { const size_t row = (size_t)(row0 + ai * HALF + m * 16); float s = 0.f;
; #pragma unroll
;                 for (int bj = 0; bj < 2; ++bj) { const size_t off = row * 1024 + col0 + bj * HALF; const u32x4 h = __builtin_nontemporal_load((const u32x4*)(XB + off));
;                     f32x4 a = acc[ai][bj][m][0], b = acc[ai][bj][m][1];
;                     a[0] += bflo(h.x); a[1] += bfhi(h.x); a[2] += bflo(h.y); a[3] += bfhi(h.y); b[0] += bflo(h.z); b[1] += bfhi(h.z); b[2] += bflo(h.w); b[3] += bfhi(h.w);
;                     s += sumsq4(a) + sumsq4(b); *(u32x4*)(HB + off) = pk8(a, b); }
;                 s += __shfl_xor(s, 16); s += __shfl_xor(s, 32);
;                 if (fq == 0) unsafeAtomicAdd(ss + row, s); }
.LBB0_699:
	s_mov_b64 s[100:101], -1
	v_lshl_add_u32 v150, s62, 8, v152
	v_lshl_or_b32 v148, s60, 8, v154
	v_ashrrev_i32_e32 v151, 31, v150
	v_ashrrev_i32_e32 v149, 31, v148
	v_lshlrev_b64 v[144:145], 10, v[150:151]
	v_lshl_add_u64 v[144:145], v[144:145], 0, v[148:149]
	v_lshlrev_b64 v[146:147], 1, v[144:145]
	v_lshl_add_u64 v[162:163], s[24:25], 0, v[146:147]
	global_load_dwordx4 v[168:171], v[162:163], off nt
	global_load_dwordx4 v[172:175], v[162:163], off offset:256 nt
	s_mov_b32 s99, 0
	s_mov_b32 s98, 0x8000
	v_lshl_add_u64 v[212:213], v[162:163], 0, s[98:99]
	global_load_dwordx4 v[176:179], v[212:213], off nt
	global_load_dwordx4 v[180:183], v[212:213], off offset:256 nt
	s_mov_b32 s98, 0x10000
	v_lshl_add_u64 v[212:213], v[162:163], 0, s[98:99]
	global_load_dwordx4 v[184:187], v[212:213], off nt
	global_load_dwordx4 v[188:191], v[212:213], off offset:256 nt
	s_mov_b32 s98, 0x18000
	v_lshl_add_u64 v[212:213], v[162:163], 0, s[98:99]
	global_load_dwordx4 v[192:195], v[212:213], off nt
	global_load_dwordx4 v[196:199], v[212:213], off offset:256 nt
	s_mov_b32 s98, 0x40000
	v_lshl_add_u64 v[212:213], v[162:163], 0, s[98:99]
	global_load_dwordx4 v[200:203], v[212:213], off nt
	global_load_dwordx4 v[204:207], v[212:213], off offset:256 nt
	s_mov_b32 s98, 0x48000
	v_lshl_add_u64 v[212:213], v[162:163], 0, s[98:99]
	global_load_dwordx4 v[208:211], v[212:213], off nt
	global_load_dwordx4 v[228:231], v[212:213], off offset:256 nt
	s_mov_b32 s98, 0x50000
	v_lshl_add_u64 v[212:213], v[162:163], 0, s[98:99]
	global_load_dwordx4 v[232:235], v[212:213], off nt
	global_load_dwordx4 v[236:239], v[212:213], off offset:256 nt
	s_mov_b32 s98, 0x58000
	v_lshl_add_u64 v[212:213], v[162:163], 0, s[98:99]
	global_load_dwordx4 v[240:243], v[212:213], off nt
	global_load_dwordx4 v[244:247], v[212:213], off offset:256 nt
	v_lshl_add_u64 v[144:145], s[14:15], 0, v[146:147]
	s_waitcnt vmcnt(15)
	v_mov_b32_e32 v158, v168
	v_mov_b32_e32 v159, v169
	v_mov_b32_e32 v160, v170
	v_mov_b32_e32 v161, v171
	v_lshlrev_b32_e32 v164, 16, v158
	v_and_b32_e32 v165, 0xffff0000, v158
	v_lshlrev_b32_e32 v158, 16, v159
	v_and_b32_e32 v159, 0xffff0000, v159
	v_lshlrev_b32_e32 v166, 16, v160
	v_and_b32_e32 v167, 0xffff0000, v160
	v_lshlrev_b32_e32 v160, 16, v161
	v_and_b32_e32 v161, 0xffff0000, v161
	v_pk_add_f32 v[124:125], v[124:125], v[164:165]
	v_pk_add_f32 v[126:127], v[126:127], v[158:159]
	v_pk_add_f32 v[158:159], v[120:121], v[166:167]
	v_pk_add_f32 v[160:161], v[122:123], v[160:161]
	v_cvt_pk_bf16_f32 v120, v124, v125
	v_cvt_pk_bf16_f32 v121, v126, v127
	v_cvt_pk_bf16_f32 v122, v158, v159
	v_cvt_pk_bf16_f32 v123, v160, v161
	global_store_dwordx4 v[144:145], v[120:123], off
	v_pk_mul_f32 v[124:125], v[124:125], v[124:125]
	v_pk_mul_f32 v[126:127], v[126:127], v[126:127]
	v_pk_mul_f32 v[158:159], v[158:159], v[158:159]
	v_pk_mul_f32 v[160:161], v[160:161], v[160:161]
	v_add_f32_e32 v158, v158, v159
	v_add_f32_e32 v160, v160, v161
	v_add_f32_e32 v126, v126, v127
	v_add_f32_e32 v124, v124, v125
	v_add_f32_e32 v125, v158, v160
	v_add_f32_e32 v124, v124, v126
	v_add_f32_e32 v158, v124, v125
	s_waitcnt vmcnt(15)
	v_mov_b32_e32 v120, v172
	v_mov_b32_e32 v121, v173
	v_mov_b32_e32 v122, v174
	v_mov_b32_e32 v123, v175
	v_lshlrev_b32_e32 v124, 16, v120
	v_and_b32_e32 v125, 0xffff0000, v120
	v_lshlrev_b32_e32 v120, 16, v121
	v_and_b32_e32 v121, 0xffff0000, v121
	v_lshlrev_b32_e32 v126, 16, v122
	v_and_b32_e32 v127, 0xffff0000, v122
	v_lshlrev_b32_e32 v122, 16, v123
	v_and_b32_e32 v123, 0xffff0000, v123
	v_pk_add_f32 v[116:117], v[116:117], v[124:125]
	v_pk_add_f32 v[118:119], v[118:119], v[120:121]
	v_pk_add_f32 v[112:113], v[112:113], v[126:127]
	v_pk_add_f32 v[114:115], v[114:115], v[122:123]
	v_pk_mul_f32 v[120:121], v[116:117], v[116:117]
	v_pk_mul_f32 v[122:123], v[118:119], v[118:119]
	v_pk_mul_f32 v[124:125], v[112:113], v[112:113]
	v_pk_mul_f32 v[126:127], v[114:115], v[114:115]
	v_add_f32_e32 v124, v124, v125
	v_add_f32_e32 v126, v126, v127
	v_add_f32_e32 v122, v122, v123
	v_add_f32_e32 v120, v120, v121
	v_add_f32_e32 v121, v124, v126
	v_add_f32_e32 v120, v120, v122
	v_add_f32_e32 v120, v120, v121
	v_add_f32_e32 v120, v158, v120
	ds_bpermute_b32 v121, v215, v120
	v_cvt_pk_bf16_f32 v116, v116, v117
	v_cvt_pk_bf16_f32 v117, v118, v119
	v_cvt_pk_bf16_f32 v119, v114, v115
	v_cvt_pk_bf16_f32 v118, v112, v113
	s_waitcnt lgkmcnt(0)
	v_add_f32_e32 v114, v120, v121
	ds_bpermute_b32 v115, v216, v114
	v_or_b32_e32 v112, 0x100, v146
	v_mov_b32_e32 v113, v147
	v_lshl_add_u64 v[112:113], s[14:15], 0, v[112:113]
	global_store_dwordx4 v[112:113], v[116:119], off
	v_lshl_add_u64 v[112:113], v[150:151], 2, s[26:27]
	s_and_saveexec_b64 s[60:61], s[4:5]
	s_cbranch_execz .LBB0_701
	s_waitcnt lgkmcnt(0)
	v_add_f32_e32 v114, v114, v115
	global_atomic_add_f32 v[112:113], v114, off

; __device__ __forceinline__ float bflo(unsigned w) { return __uint_as_float(w << 16); }
; __device__ __forceinline__ float bfhi(unsigned w) { return __uint_as_float(w & 0xffff0000u); }
; __device__ __forceinline__ u32x4 pk8(const f32x4 a, const f32x4 b) { u32x4 w; w.x = pkbf(a[0], a[1]); w.y = pkbf(a[2], a[3]); w.z = pkbf(b[0], b[1]); w.w = pkbf(b[2], b[3]); return w; }
; __device__ __forceinline__ float sumsq4(const f32x4 a) { return (a[0] * a[0] + a[1] * a[1]) + (a[2] * a[2] + a[3] * a[3]); }
;     __device__ __forceinline__ void operator()(const f32x4 (&acc)[2][2][4][2], const Unit& u, int wr, int wc, int fr, int fq) const {
;         const int row0 = u.pm * BM + wr * 64 + fr, col0 = u.pn * BM + wc * 32 + 8 * fq;
; #pragma unroll
;         for (int ai = 0; ai < 2; ++ai)
; #pragma unroll
;             for (int m = 0; m < 4; ++m) { const size_t row = (size_t)(row0 + ai * HALF + m * 16); float s = 0.f;
; #pragma unroll
;                 for (int bj = 0; bj < 2; ++bj) { const size_t off = row * 1024 + col0 + bj * HALF; const u32x4 h = __builtin_nontemporal_load((const u32x4*)(HB + off));
;                     f32x4 a = acc[ai][bj][m][0], b = acc[ai][bj][m][1];
;                     a[0] += bflo(h.x); a[1] += bfhi(h.x); a[2] += bflo(h.y); a[3] += bfhi(h.y); b[0] += bflo(h.z); b[1] += bfhi(h.z); b[2] += bflo(h.w); b[3] += bfhi(h.w);
;                     s += sumsq4(a) + sumsq4(b); *(u32x4*)(HO + off) = pk8(a, b); }
;                 s += __shfl_xor(s, 16); s += __shfl_xor(s, 32);
;                 if (fq == 0) unsafeAtomicAdd(ss + row, s); }
.LBB0_859:
	s_mov_b64 s[100:101], -1
	v_lshl_add_u32 v146, s46, 8, v148
	v_ashrrev_i32_e32 v147, 31, v146
	v_lshl_or_b32 v144, s44, 8, v150
	v_lshlrev_b64 v[154:155], 11, v[146:147]
	v_ashrrev_i32_e32 v145, 31, v144
	v_lshl_add_u64 v[154:155], s[14:15], 0, v[154:155]
	v_lshl_add_u64 v[162:163], v[144:145], 1, v[154:155]
	global_load_dwordx4 v[172:175], v[162:163], off nt
	global_load_dwordx4 v[176:179], v[162:163], off offset:256 nt
	s_mov_b32 s99, 0
	s_mov_b32 s98, 0x8000
	v_lshl_add_u64 v[212:213], v[162:163], 0, s[98:99]
	global_load_dwordx4 v[180:183], v[212:213], off nt
	global_load_dwordx4 v[184:187], v[212:213], off offset:256 nt
	s_mov_b32 s98, 0x10000
	v_lshl_add_u64 v[212:213], v[162:163], 0, s[98:99]
	global_load_dwordx4 v[188:191], v[212:213], off nt
	global_load_dwordx4 v[192:195], v[212:213], off offset:256 nt
	s_mov_b32 s98, 0x18000
	v_lshl_add_u64 v[212:213], v[162:163], 0, s[98:99]
	global_load_dwordx4 v[196:199], v[212:213], off nt
	global_load_dwordx4 v[200:203], v[212:213], off offset:256 nt
	s_mov_b32 s98, 0x40000
	v_lshl_add_u64 v[212:213], v[162:163], 0, s[98:99]
	global_load_dwordx4 v[204:207], v[212:213], off nt
	global_load_dwordx4 v[208:211], v[212:213], off offset:256 nt
	s_mov_b32 s98, 0x48000
	v_lshl_add_u64 v[212:213], v[162:163], 0, s[98:99]
	global_load_dwordx4 v[228:231], v[212:213], off nt
	global_load_dwordx4 v[232:235], v[212:213], off offset:256 nt
	s_mov_b32 s98, 0x50000
	v_lshl_add_u64 v[212:213], v[162:163], 0, s[98:99]
	global_load_dwordx4 v[236:239], v[212:213], off nt
	global_load_dwordx4 v[240:243], v[212:213], off offset:256 nt
	s_mov_b32 s98, 0x58000
	v_lshl_add_u64 v[212:213], v[162:163], 0, s[98:99]
	global_load_dwordx4 v[244:247], v[212:213], off nt
	global_load_dwordx4 v[248:251], v[212:213], off offset:256 nt
	s_waitcnt vmcnt(14)
	v_mov_b32_e32 v154, v172
	v_mov_b32_e32 v155, v173
	v_mov_b32_e32 v156, v174
	v_mov_b32_e32 v157, v175
	v_mov_b32_e32 v158, v176
	v_mov_b32_e32 v159, v177
	v_mov_b32_e32 v160, v178
	v_mov_b32_e32 v161, v179
	v_lshlrev_b32_e32 v164, 16, v154
	v_and_b32_e32 v165, 0xffff0000, v154
	v_lshlrev_b32_e32 v154, 16, v155
	v_and_b32_e32 v155, 0xffff0000, v155
	v_lshlrev_b32_e32 v166, 16, v156
	v_and_b32_e32 v167, 0xffff0000, v156
	v_lshlrev_b32_e32 v156, 16, v157
	v_and_b32_e32 v157, 0xffff0000, v157
	v_lshlrev_b32_e32 v168, 16, v158
	v_and_b32_e32 v169, 0xffff0000, v158
	v_lshlrev_b32_e32 v158, 16, v159
	v_and_b32_e32 v159, 0xffff0000, v159
	v_lshlrev_b32_e32 v170, 16, v160
	v_and_b32_e32 v171, 0xffff0000, v160
	v_lshlrev_b32_e32 v160, 16, v161
	v_and_b32_e32 v161, 0xffff0000, v161
	v_pk_add_f32 v[124:125], v[124:125], v[164:165]
	v_pk_add_f32 v[126:127], v[126:127], v[154:155]
	v_pk_add_f32 v[120:121], v[120:121], v[166:167]
	v_pk_add_f32 v[122:123], v[122:123], v[156:157]
	v_pk_add_f32 v[116:117], v[116:117], v[168:169]
	v_pk_add_f32 v[118:119], v[118:119], v[158:159]
	v_pk_add_f32 v[154:155], v[112:113], v[170:171]
	v_pk_add_f32 v[156:157], v[114:115], v[160:161]
	v_pk_mul_f32 v[114:115], v[124:125], v[124:125]
	v_pk_mul_f32 v[158:159], v[126:127], v[126:127]
	v_pk_mul_f32 v[160:161], v[120:121], v[120:121]
	v_pk_mul_f32 v[164:165], v[122:123], v[122:123]
	v_cvt_pk_bf16_f32 v112, v124, v125
	v_cvt_pk_bf16_f32 v113, v126, v127
	v_pk_mul_f32 v[124:125], v[116:117], v[116:117]
	v_pk_mul_f32 v[126:127], v[118:119], v[118:119]
	v_pk_mul_f32 v[166:167], v[154:155], v[154:155]
	v_pk_mul_f32 v[168:169], v[156:157], v[156:157]
	v_add_f32_e32 v166, v166, v167
	v_add_f32_e32 v168, v168, v169
	v_add_f32_e32 v126, v126, v127
	v_add_f32_e32 v124, v124, v125
	v_add_f32_e32 v125, v164, v165
	v_add_f32_e32 v127, v160, v161
	v_add_f32_e32 v158, v158, v159
	v_add_f32_e32 v114, v114, v115
	v_add_f32_e32 v115, v166, v168
	v_add_f32_e32 v124, v124, v126
	v_add_f32_e32 v125, v127, v125
	v_add_f32_e32 v114, v114, v158
	v_add_f32_e32 v115, v124, v115
	v_add_f32_e32 v114, v114, v125
	v_add_f32_e32 v124, v114, v115
	ds_bpermute_b32 v125, v215, v124
	v_cvt_pk_bf16_f32 v114, v120, v121
	v_cvt_pk_bf16_f32 v115, v122, v123
	global_store_dwordx4 v[162:163], v[112:115], off
	s_waitcnt lgkmcnt(0)
	s_nop 0
	v_add_f32_e32 v112, v124, v125
	ds_bpermute_b32 v113, v216, v112
	v_cvt_pk_bf16_f32 v114, v116, v117
	v_cvt_pk_bf16_f32 v115, v118, v119
	v_cvt_pk_bf16_f32 v116, v154, v155
	v_cvt_pk_bf16_f32 v117, v156, v157
	global_store_dwordx4 v[162:163], v[114:117], off offset:256
	s_and_saveexec_b64 s[44:45], s[2:3]
	s_cbranch_execz .LBB0_861
	v_lshl_add_u64 v[114:115], v[146:147], 2, s[0:1]
	s_waitcnt lgkmcnt(0)
	v_add_f32_e32 v112, v112, v113
	global_atomic_add_f32 v[114:115], v112, off
